# GLA pass-2 segment-state fold loop rewritten with 60 loads in flight (counted vmcnt), on top of re-ordered prefetch + pipelined step 4
# speedup vs baseline: 1.0104x; 1.0039x over previous
; __device__ __forceinline__ int crow(int r,int hi){return (r&3)+8*(r>>2)+4*hi;}
; __device__ __forceinline__ int crow(int r, int hi) { return (r & 3) + 8 * (r >> 2) + 4 * hi; }
; template <int MODE> __device__ __forceinline__ void chain(int b, int h, int seg, float* __restrict__ SLOC, float* __restrict__ DTOT, const bf16_t* __restrict__ QB, const bf16_t* __restrict__ KB, const bf16_t* __restrict__ VB, bf16_t* __restrict__ OB, const bf16_t* __restrict__ RB, const float* __res ...
;     ...
;     if (MODE == 1) {
;         for (int g = 0; g < seg; ++g) { const float* sl = SLOC + ((size_t)((b * 4 + h) * 8 + g) * 128) * 256; const float* dd = DTOT + ((b * 4 + h) * 8 + g) * 128;
; #pragma unroll
;             for (int cb = 0; cb < 4; ++cb)
; #pragma unroll
;                 for (int r = 0; r < 16; ++r) { const int c = 32 * cb + crow(r, hi); S[cb][r] = __expf(dd[c]) * S[cb][r] + sl[(size_t)c * 256 + 32 * wid + r32]; } }
.LBB0_670:
	v_lshl_add_u64 v[8:9], s[8:9], 2, v[4:5]
	global_load_dwordx4 v[96:99], v[8:9], off
	global_load_dword v100, v[6:7], off
	global_load_dword v101, v[6:7], off offset:1024
	global_load_dword v102, v[6:7], off offset:2048
	global_load_dword v103, v[6:7], off offset:3072
	global_load_dwordx4 v[104:107], v[8:9], off offset:32
	v_add_co_u32_e32 v10, vcc, 0x2000, v6
	s_nop 1
	v_addc_co_u32_e32 v11, vcc, 0, v7, vcc
	global_load_dword v108, v[10:11], off
	global_load_dword v109, v[10:11], off offset:1024
	global_load_dword v110, v[10:11], off offset:2048
	global_load_dword v111, v[10:11], off offset:3072
	global_load_dwordx4 v[112:115], v[8:9], off offset:64
	v_add_co_u32_e32 v10, vcc, 0x4000, v6
	s_nop 1
	v_addc_co_u32_e32 v11, vcc, 0, v7, vcc
	global_load_dword v116, v[10:11], off
	global_load_dword v117, v[10:11], off offset:1024
	global_load_dword v118, v[10:11], off offset:2048
	global_load_dword v119, v[10:11], off offset:3072
	global_load_dwordx4 v[120:123], v[8:9], off offset:96
	v_add_co_u32_e32 v10, vcc, 0x6000, v6
	s_nop 1
	v_addc_co_u32_e32 v11, vcc, 0, v7, vcc
	global_load_dword v124, v[10:11], off
	global_load_dword v125, v[10:11], off offset:1024
	global_load_dword v126, v[10:11], off offset:2048
	global_load_dword v127, v[10:11], off offset:3072
	global_load_dwordx4 v[148:151], v[8:9], off offset:128
	v_add_co_u32_e32 v10, vcc, 0x8000, v6
	s_nop 1
	v_addc_co_u32_e32 v11, vcc, 0, v7, vcc
	global_load_dword v152, v[10:11], off
	global_load_dword v153, v[10:11], off offset:1024
	global_load_dword v154, v[10:11], off offset:2048
	global_load_dword v155, v[10:11], off offset:3072
	global_load_dwordx4 v[156:159], v[8:9], off offset:160
	v_add_co_u32_e32 v10, vcc, 0xa000, v6
	s_nop 1
	v_addc_co_u32_e32 v11, vcc, 0, v7, vcc
	global_load_dword v160, v[10:11], off
	global_load_dword v161, v[10:11], off offset:1024
	global_load_dword v162, v[10:11], off offset:2048
	global_load_dword v163, v[10:11], off offset:3072
	global_load_dwordx4 v[164:167], v[8:9], off offset:192
	v_add_co_u32_e32 v10, vcc, 0xc000, v6
	s_nop 1
	v_addc_co_u32_e32 v11, vcc, 0, v7, vcc
	global_load_dword v168, v[10:11], off
	global_load_dword v169, v[10:11], off offset:1024
	global_load_dword v170, v[10:11], off offset:2048
	global_load_dword v171, v[10:11], off offset:3072
	global_load_dwordx4 v[172:175], v[8:9], off offset:224
	v_add_co_u32_e32 v10, vcc, 0xe000, v6
	s_nop 1
	v_addc_co_u32_e32 v11, vcc, 0, v7, vcc
	global_load_dword v176, v[10:11], off
	global_load_dword v177, v[10:11], off offset:1024
	global_load_dword v178, v[10:11], off offset:2048
	global_load_dword v179, v[10:11], off offset:3072
	global_load_dwordx4 v[192:195], v[8:9], off offset:256
	v_add_co_u32_e32 v10, vcc, 0x10000, v6
	s_nop 1
	v_addc_co_u32_e32 v11, vcc, 0, v7, vcc
	global_load_dword v196, v[10:11], off
	global_load_dword v197, v[10:11], off offset:1024
	global_load_dword v198, v[10:11], off offset:2048
	global_load_dword v199, v[10:11], off offset:3072
	global_load_dwordx4 v[200:203], v[8:9], off offset:288
	v_add_co_u32_e32 v10, vcc, 0x12000, v6
	s_nop 1
	v_addc_co_u32_e32 v11, vcc, 0, v7, vcc
	global_load_dword v204, v[10:11], off
	global_load_dword v205, v[10:11], off offset:1024
	global_load_dword v206, v[10:11], off offset:2048
	global_load_dword v207, v[10:11], off offset:3072
	global_load_dwordx4 v[208:211], v[8:9], off offset:320
	v_add_co_u32_e32 v10, vcc, 0x14000, v6
	s_nop 1
	v_addc_co_u32_e32 v11, vcc, 0, v7, vcc
	global_load_dword v212, v[10:11], off
	global_load_dword v213, v[10:11], off offset:1024
	global_load_dword v214, v[10:11], off offset:2048
	global_load_dword v215, v[10:11], off offset:3072
	global_load_dwordx4 v[216:219], v[8:9], off offset:352
	v_add_co_u32_e32 v10, vcc, 0x16000, v6
	s_nop 1
	v_addc_co_u32_e32 v11, vcc, 0, v7, vcc
	global_load_dword v220, v[10:11], off
	global_load_dword v221, v[10:11], off offset:1024
	global_load_dword v222, v[10:11], off offset:2048
	global_load_dword v223, v[10:11], off offset:3072
	s_waitcnt vmcnt(59)
	v_mul_f32_e32 v2, 0x3fb8aa3b, v96
	v_exp_f32_e32 v96, v2
	v_mul_f32_e32 v2, 0x3fb8aa3b, v97
	v_exp_f32_e32 v97, v2
	v_mul_f32_e32 v2, 0x3fb8aa3b, v98
	v_exp_f32_e32 v98, v2
	v_mul_f32_e32 v2, 0x3fb8aa3b, v99
	v_exp_f32_e32 v99, v2
	s_waitcnt vmcnt(55)
	v_pk_fma_f32 v[66:67], v[66:67], v[96:97], v[100:101]
	v_pk_fma_f32 v[68:69], v[68:69], v[98:99], v[102:103]
	global_load_dwordx4 v[96:99], v[8:9], off offset:384
	v_add_co_u32_e32 v10, vcc, 0x18000, v6
	s_nop 1
	v_addc_co_u32_e32 v11, vcc, 0, v7, vcc
	global_load_dword v100, v[10:11], off
	global_load_dword v101, v[10:11], off offset:1024
	global_load_dword v102, v[10:11], off offset:2048
	global_load_dword v103, v[10:11], off offset:3072
	s_waitcnt vmcnt(59)
	v_mul_f32_e32 v2, 0x3fb8aa3b, v104
	v_exp_f32_e32 v104, v2
	v_mul_f32_e32 v2, 0x3fb8aa3b, v105
	v_exp_f32_e32 v105, v2
	v_mul_f32_e32 v2, 0x3fb8aa3b, v106
	v_exp_f32_e32 v106, v2
	v_mul_f32_e32 v2, 0x3fb8aa3b, v107
	v_exp_f32_e32 v107, v2
	s_waitcnt vmcnt(55)
	v_pk_fma_f32 v[70:71], v[70:71], v[104:105], v[108:109]
	v_pk_fma_f32 v[72:73], v[72:73], v[106:107], v[110:111]
	global_load_dwordx4 v[104:107], v[8:9], off offset:416
	v_add_co_u32_e32 v10, vcc, 0x1a000, v6
	s_nop 1
	v_addc_co_u32_e32 v11, vcc, 0, v7, vcc
	global_load_dword v108, v[10:11], off
	global_load_dword v109, v[10:11], off offset:1024
	global_load_dword v110, v[10:11], off offset:2048
	global_load_dword v111, v[10:11], off offset:3072
	s_waitcnt vmcnt(59)
	v_mul_f32_e32 v2, 0x3fb8aa3b, v112
	v_exp_f32_e32 v112, v2
	v_mul_f32_e32 v2, 0x3fb8aa3b, v113
	v_exp_f32_e32 v113, v2
	v_mul_f32_e32 v2, 0x3fb8aa3b, v114
	v_exp_f32_e32 v114, v2
	v_mul_f32_e32 v2, 0x3fb8aa3b, v115
	v_exp_f32_e32 v115, v2
	s_waitcnt vmcnt(55)
; __device__ __forceinline__ int crow(int r,int hi){return (r&3)+8*(r>>2)+4*hi;}
; __device__ __forceinline__ int crow(int r, int hi) { return (r & 3) + 8 * (r >> 2) + 4 * hi; }
; template <int MODE> __device__ __forceinline__ void chain(int b, int h, int seg, float* __restrict__ SLOC, float* __restrict__ DTOT, const bf16_t* __restrict__ QB, const bf16_t* __restrict__ KB, const bf16_t* __restrict__ VB, bf16_t* __restrict__ OB, const bf16_t* __restrict__ RB, const float* __res ...
;     ...
;     if (MODE == 1) {
;         for (int g = 0; g < seg; ++g) { const float* sl = SLOC + ((size_t)((b * 4 + h) * 8 + g) * 128) * 256; const float* dd = DTOT + ((b * 4 + h) * 8 + g) * 128;
; #pragma unroll
;             for (int cb = 0; cb < 4; ++cb)
; #pragma unroll
;                 for (int r = 0; r < 16; ++r) { const int c = 32 * cb + crow(r, hi); S[cb][r] = __expf(dd[c]) * S[cb][r] + sl[(size_t)c * 256 + 32 * wid + r32]; } }
	v_pk_fma_f32 v[74:75], v[74:75], v[112:113], v[116:117]
	v_pk_fma_f32 v[76:77], v[76:77], v[114:115], v[118:119]
	global_load_dwordx4 v[112:115], v[8:9], off offset:448
	v_add_co_u32_e32 v10, vcc, 0x1c000, v6
	s_nop 1
	v_addc_co_u32_e32 v11, vcc, 0, v7, vcc
	global_load_dword v116, v[10:11], off
	global_load_dword v117, v[10:11], off offset:1024
	global_load_dword v118, v[10:11], off offset:2048
	global_load_dword v119, v[10:11], off offset:3072
	s_waitcnt vmcnt(59)
	v_mul_f32_e32 v2, 0x3fb8aa3b, v120
	v_exp_f32_e32 v120, v2
	v_mul_f32_e32 v2, 0x3fb8aa3b, v121
	v_exp_f32_e32 v121, v2
	v_mul_f32_e32 v2, 0x3fb8aa3b, v122
	v_exp_f32_e32 v122, v2
	v_mul_f32_e32 v2, 0x3fb8aa3b, v123
	v_exp_f32_e32 v123, v2
	s_waitcnt vmcnt(55)
	v_pk_fma_f32 v[78:79], v[78:79], v[120:121], v[124:125]
	v_pk_fma_f32 v[80:81], v[80:81], v[122:123], v[126:127]
	global_load_dwordx4 v[120:123], v[8:9], off offset:480
	v_add_co_u32_e32 v10, vcc, 0x1e000, v6
	s_nop 1
	v_addc_co_u32_e32 v11, vcc, 0, v7, vcc
	global_load_dword v124, v[10:11], off
	global_load_dword v125, v[10:11], off offset:1024
	global_load_dword v126, v[10:11], off offset:2048
	global_load_dword v127, v[10:11], off offset:3072
	s_waitcnt vmcnt(59)
	v_mul_f32_e32 v2, 0x3fb8aa3b, v148
	v_exp_f32_e32 v148, v2
	v_mul_f32_e32 v2, 0x3fb8aa3b, v149
	v_exp_f32_e32 v149, v2
	v_mul_f32_e32 v2, 0x3fb8aa3b, v150
	v_exp_f32_e32 v150, v2
	v_mul_f32_e32 v2, 0x3fb8aa3b, v151
	v_exp_f32_e32 v151, v2
	s_waitcnt vmcnt(55)
	v_pk_fma_f32 v[50:51], v[50:51], v[148:149], v[152:153]
	v_pk_fma_f32 v[52:53], v[52:53], v[150:151], v[154:155]
	s_waitcnt vmcnt(54)
	v_mul_f32_e32 v2, 0x3fb8aa3b, v156
	v_exp_f32_e32 v156, v2
	v_mul_f32_e32 v2, 0x3fb8aa3b, v157
	v_exp_f32_e32 v157, v2
	v_mul_f32_e32 v2, 0x3fb8aa3b, v158
	v_exp_f32_e32 v158, v2
	v_mul_f32_e32 v2, 0x3fb8aa3b, v159
	v_exp_f32_e32 v159, v2
	s_waitcnt vmcnt(50)
	v_pk_fma_f32 v[54:55], v[54:55], v[156:157], v[160:161]
	v_pk_fma_f32 v[56:57], v[56:57], v[158:159], v[162:163]
	s_waitcnt vmcnt(49)
	v_mul_f32_e32 v2, 0x3fb8aa3b, v164
	v_exp_f32_e32 v164, v2
	v_mul_f32_e32 v2, 0x3fb8aa3b, v165
	v_exp_f32_e32 v165, v2
	v_mul_f32_e32 v2, 0x3fb8aa3b, v166
	v_exp_f32_e32 v166, v2
	v_mul_f32_e32 v2, 0x3fb8aa3b, v167
	v_exp_f32_e32 v167, v2
	s_waitcnt vmcnt(45)
	v_pk_fma_f32 v[58:59], v[58:59], v[164:165], v[168:169]
	v_pk_fma_f32 v[60:61], v[60:61], v[166:167], v[170:171]
	s_waitcnt vmcnt(44)
	v_mul_f32_e32 v2, 0x3fb8aa3b, v172
	v_exp_f32_e32 v172, v2
	v_mul_f32_e32 v2, 0x3fb8aa3b, v173
	v_exp_f32_e32 v173, v2
	v_mul_f32_e32 v2, 0x3fb8aa3b, v174
	v_exp_f32_e32 v174, v2
	v_mul_f32_e32 v2, 0x3fb8aa3b, v175
	v_exp_f32_e32 v175, v2
	s_waitcnt vmcnt(40)
	v_pk_fma_f32 v[62:63], v[62:63], v[172:173], v[176:177]
	v_pk_fma_f32 v[64:65], v[64:65], v[174:175], v[178:179]
	s_waitcnt vmcnt(39)
	v_mul_f32_e32 v2, 0x3fb8aa3b, v192
	v_exp_f32_e32 v192, v2
	v_mul_f32_e32 v2, 0x3fb8aa3b, v193
	v_exp_f32_e32 v193, v2
	v_mul_f32_e32 v2, 0x3fb8aa3b, v194
	v_exp_f32_e32 v194, v2
	v_mul_f32_e32 v2, 0x3fb8aa3b, v195
	v_exp_f32_e32 v195, v2
	s_waitcnt vmcnt(35)
	v_pk_fma_f32 v[34:35], v[34:35], v[192:193], v[196:197]
	v_pk_fma_f32 v[36:37], v[36:37], v[194:195], v[198:199]
	s_waitcnt vmcnt(34)
	v_mul_f32_e32 v2, 0x3fb8aa3b, v200
	v_exp_f32_e32 v200, v2
	v_mul_f32_e32 v2, 0x3fb8aa3b, v201
	v_exp_f32_e32 v201, v2
	v_mul_f32_e32 v2, 0x3fb8aa3b, v202
	v_exp_f32_e32 v202, v2
	v_mul_f32_e32 v2, 0x3fb8aa3b, v203
	v_exp_f32_e32 v203, v2
	s_waitcnt vmcnt(30)
	v_pk_fma_f32 v[38:39], v[38:39], v[200:201], v[204:205]
	v_pk_fma_f32 v[40:41], v[40:41], v[202:203], v[206:207]
	s_waitcnt vmcnt(29)
	v_mul_f32_e32 v2, 0x3fb8aa3b, v208
	v_exp_f32_e32 v208, v2
	v_mul_f32_e32 v2, 0x3fb8aa3b, v209
	v_exp_f32_e32 v209, v2
	v_mul_f32_e32 v2, 0x3fb8aa3b, v210
	v_exp_f32_e32 v210, v2
	v_mul_f32_e32 v2, 0x3fb8aa3b, v211
	v_exp_f32_e32 v211, v2
	s_waitcnt vmcnt(25)
	v_pk_fma_f32 v[42:43], v[42:43], v[208:209], v[212:213]
	v_pk_fma_f32 v[44:45], v[44:45], v[210:211], v[214:215]
	s_waitcnt vmcnt(24)
	v_mul_f32_e32 v2, 0x3fb8aa3b, v216
	v_exp_f32_e32 v216, v2
	v_mul_f32_e32 v2, 0x3fb8aa3b, v217
	v_exp_f32_e32 v217, v2
	v_mul_f32_e32 v2, 0x3fb8aa3b, v218
	v_exp_f32_e32 v218, v2
	v_mul_f32_e32 v2, 0x3fb8aa3b, v219
	v_exp_f32_e32 v219, v2
	s_waitcnt vmcnt(20)
	v_pk_fma_f32 v[46:47], v[46:47], v[216:217], v[220:221]
	v_pk_fma_f32 v[48:49], v[48:49], v[218:219], v[222:223]
	s_waitcnt vmcnt(19)
	v_mul_f32_e32 v2, 0x3fb8aa3b, v96
	v_exp_f32_e32 v96, v2
	v_mul_f32_e32 v2, 0x3fb8aa3b, v97
	v_exp_f32_e32 v97, v2
	v_mul_f32_e32 v2, 0x3fb8aa3b, v98
	v_exp_f32_e32 v98, v2
	v_mul_f32_e32 v2, 0x3fb8aa3b, v99
	v_exp_f32_e32 v99, v2
	s_waitcnt vmcnt(15)
	v_pk_fma_f32 v[18:19], v[18:19], v[96:97], v[100:101]
	v_pk_fma_f32 v[20:21], v[20:21], v[98:99], v[102:103]
	s_waitcnt vmcnt(14)
	v_mul_f32_e32 v2, 0x3fb8aa3b, v104
	v_exp_f32_e32 v104, v2
	v_mul_f32_e32 v2, 0x3fb8aa3b, v105
	v_exp_f32_e32 v105, v2
	v_mul_f32_e32 v2, 0x3fb8aa3b, v106
	v_exp_f32_e32 v106, v2
	v_mul_f32_e32 v2, 0x3fb8aa3b, v107
	v_exp_f32_e32 v107, v2
	s_waitcnt vmcnt(10)
	v_pk_fma_f32 v[22:23], v[22:23], v[104:105], v[108:109]
	v_pk_fma_f32 v[24:25], v[24:25], v[106:107], v[110:111]
	s_waitcnt vmcnt(9)
	v_mul_f32_e32 v2, 0x3fb8aa3b, v112
	v_exp_f32_e32 v112, v2
	v_mul_f32_e32 v2, 0x3fb8aa3b, v113
	v_exp_f32_e32 v113, v2
	v_mul_f32_e32 v2, 0x3fb8aa3b, v114
	v_exp_f32_e32 v114, v2
	v_mul_f32_e32 v2, 0x3fb8aa3b, v115
	v_exp_f32_e32 v115, v2
	s_waitcnt vmcnt(5)
	v_pk_fma_f32 v[26:27], v[26:27], v[112:113], v[116:117]
	v_pk_fma_f32 v[28:29], v[28:29], v[114:115], v[118:119]
	s_waitcnt vmcnt(4)
	v_mul_f32_e32 v2, 0x3fb8aa3b, v120
	v_exp_f32_e32 v120, v2
	v_mul_f32_e32 v2, 0x3fb8aa3b, v121
	v_exp_f32_e32 v121, v2
	v_mul_f32_e32 v2, 0x3fb8aa3b, v122
	v_exp_f32_e32 v122, v2
	v_mul_f32_e32 v2, 0x3fb8aa3b, v123
	v_exp_f32_e32 v123, v2
	s_waitcnt vmcnt(0)
	v_pk_fma_f32 v[30:31], v[30:31], v[120:121], v[124:125]
	v_pk_fma_f32 v[32:33], v[32:33], v[122:123], v[126:127]
	s_mov_b64 s[12:13], 0x20000
	v_lshl_add_u64 v[6:7], v[6:7], 0, s[12:13]
	s_addk_i32 s8, 0x80
	s_add_i32 s4, s4, -1
	s_cmp_eq_u32 s4, 0
	s_cbranch_scc0 .LBB0_670
	s_branch .LBB0_672
